# attention value waves: staging halves rotated so each half has about half a tile of latency cover (first half prefetched at the end of the previous iteration)
# speedup vs baseline: 1.0251x; 1.0026x over previous
.LBB0_397:
	s_add_i32 s8, s19, 2
	s_mul_hi_u32 s9, s8, 0xaaaaaaab
	s_lshr_b32 s9, s9, 1
	s_mul_i32 s9, s9, 3
	s_sub_i32 s8, s8, s9
	s_mul_i32 s8, s8, 0xa400
	v_add_u32_e32 v145, s8, v170
	s_lshl_b32 s8, s30, 2
	s_add_i32 s8, s8, -4
	s_and_b32 s8, s8, 4
	v_readlane_b32 s9, v255, 28
	s_or_b32 s8, s8, s9
	s_mulk_i32 s8, 0x1080
	s_add_i32 s8, s8, 0x1ec00
	v_add_u32_e32 v0, s8, v168
	ds_read_b32 v0, v0 offset:4096
	s_bfe_u32 s8, s18, 0x10002
	s_mulk_i32 s8, 0x4200
	s_add_i32 s8, s8, 0xfffffc00
	v_add_u32_e32 v2, s8, v172
	s_mul_hi_u32 s8, s19, 0xaaaaaaab
	s_lshr_b32 s8, s8, 1
	s_mul_i32 s8, s8, 0xfffe1400
	s_add_i32 s8, s8, 0xffff5c00
	v_add_u32_e32 v3, s8, v144
	ds_read_b128 v[176:179], v2
	ds_read_b128 v[180:183], v2 offset:1024
	ds_read_b128 v[184:187], v2 offset:2048
	ds_read_b128 v[188:191], v2 offset:3072
	ds_read_b64_tr_b16 v[220:221], v3
	ds_read_b64_tr_b16 v[222:223], v3 offset:5248
	ds_read_b64_tr_b16 v[224:225], v3 offset:64
	ds_read_b64_tr_b16 v[226:227], v3 offset:5312
	ds_read_b64_tr_b16 v[228:229], v3 offset:128
	ds_read_b64_tr_b16 v[230:231], v3 offset:5376
	ds_read_b64_tr_b16 v[232:233], v3 offset:192
	ds_read_b64_tr_b16 v[234:235], v3 offset:5440
	ds_read_b64_tr_b16 v[236:237], v3 offset:256
	ds_read_b64_tr_b16 v[238:239], v3 offset:5504
	s_waitcnt lgkmcnt(14)
	v_cmp_neq_f32_e32 vcc, 1.0, v0
	s_cbranch_vccz .Lav_noscale
	v_pk_mul_f32 v[142:143], v[0:1], v[142:143] op_sel_hi:[0,1]
	v_pk_mul_f32 v[140:141], v[0:1], v[140:141] op_sel_hi:[0,1]
	v_pk_mul_f32 v[138:139], v[0:1], v[138:139] op_sel_hi:[0,1]
	v_pk_mul_f32 v[136:137], v[0:1], v[136:137] op_sel_hi:[0,1]
	v_pk_mul_f32 v[134:135], v[0:1], v[134:135] op_sel_hi:[0,1]
	v_pk_mul_f32 v[132:133], v[0:1], v[132:133] op_sel_hi:[0,1]
	v_pk_mul_f32 v[130:131], v[0:1], v[130:131] op_sel_hi:[0,1]
	v_pk_mul_f32 v[128:129], v[0:1], v[128:129] op_sel_hi:[0,1]
	v_pk_mul_f32 v[126:127], v[0:1], v[126:127] op_sel_hi:[0,1]
	v_pk_mul_f32 v[124:125], v[0:1], v[124:125] op_sel_hi:[0,1]
	v_pk_mul_f32 v[122:123], v[0:1], v[122:123] op_sel_hi:[0,1]
	v_pk_mul_f32 v[120:121], v[0:1], v[120:121] op_sel_hi:[0,1]
	v_pk_mul_f32 v[118:119], v[0:1], v[118:119] op_sel_hi:[0,1]
	v_pk_mul_f32 v[116:117], v[0:1], v[116:117] op_sel_hi:[0,1]
	v_pk_mul_f32 v[114:115], v[0:1], v[114:115] op_sel_hi:[0,1]
	v_pk_mul_f32 v[112:113], v[0:1], v[112:113] op_sel_hi:[0,1]
	v_pk_mul_f32 v[110:111], v[0:1], v[110:111] op_sel_hi:[0,1]
	v_pk_mul_f32 v[108:109], v[0:1], v[108:109] op_sel_hi:[0,1]
	v_pk_mul_f32 v[106:107], v[0:1], v[106:107] op_sel_hi:[0,1]
	v_pk_mul_f32 v[104:105], v[0:1], v[104:105] op_sel_hi:[0,1]
	v_pk_mul_f32 v[102:103], v[0:1], v[102:103] op_sel_hi:[0,1]
	v_pk_mul_f32 v[100:101], v[0:1], v[100:101] op_sel_hi:[0,1]
	v_pk_mul_f32 v[98:99], v[0:1], v[98:99] op_sel_hi:[0,1]
	v_pk_mul_f32 v[96:97], v[0:1], v[96:97] op_sel_hi:[0,1]
	v_pk_mul_f32 v[94:95], v[0:1], v[94:95] op_sel_hi:[0,1]
	v_pk_mul_f32 v[92:93], v[0:1], v[92:93] op_sel_hi:[0,1]
	v_pk_mul_f32 v[90:91], v[0:1], v[90:91] op_sel_hi:[0,1]
	v_pk_mul_f32 v[88:89], v[0:1], v[88:89] op_sel_hi:[0,1]
	v_pk_mul_f32 v[86:87], v[0:1], v[86:87] op_sel_hi:[0,1]
	v_pk_mul_f32 v[84:85], v[0:1], v[84:85] op_sel_hi:[0,1]
	v_pk_mul_f32 v[82:83], v[0:1], v[82:83] op_sel_hi:[0,1]
	v_pk_mul_f32 v[80:81], v[0:1], v[80:81] op_sel_hi:[0,1]
	v_pk_mul_f32 v[78:79], v[0:1], v[78:79] op_sel_hi:[0,1]
	v_pk_mul_f32 v[76:77], v[0:1], v[76:77] op_sel_hi:[0,1]
	v_pk_mul_f32 v[74:75], v[0:1], v[74:75] op_sel_hi:[0,1]
	v_pk_mul_f32 v[72:73], v[0:1], v[72:73] op_sel_hi:[0,1]
	v_pk_mul_f32 v[70:71], v[0:1], v[70:71] op_sel_hi:[0,1]
	v_pk_mul_f32 v[68:69], v[0:1], v[68:69] op_sel_hi:[0,1]
	v_pk_mul_f32 v[66:67], v[0:1], v[66:67] op_sel_hi:[0,1]
	v_pk_mul_f32 v[64:65], v[0:1], v[64:65] op_sel_hi:[0,1]
	v_pk_mul_f32 v[62:63], v[0:1], v[62:63] op_sel_hi:[0,1]
	v_pk_mul_f32 v[60:61], v[0:1], v[60:61] op_sel_hi:[0,1]
	v_pk_mul_f32 v[58:59], v[0:1], v[58:59] op_sel_hi:[0,1]
	v_pk_mul_f32 v[56:57], v[0:1], v[56:57] op_sel_hi:[0,1]
	v_pk_mul_f32 v[54:55], v[0:1], v[54:55] op_sel_hi:[0,1]
	v_pk_mul_f32 v[52:53], v[0:1], v[52:53] op_sel_hi:[0,1]
	v_pk_mul_f32 v[50:51], v[0:1], v[50:51] op_sel_hi:[0,1]
	v_pk_mul_f32 v[48:49], v[0:1], v[48:49] op_sel_hi:[0,1]
	v_pk_mul_f32 v[46:47], v[0:1], v[46:47] op_sel_hi:[0,1]
	v_pk_mul_f32 v[44:45], v[0:1], v[44:45] op_sel_hi:[0,1]
	v_pk_mul_f32 v[42:43], v[0:1], v[42:43] op_sel_hi:[0,1]
	v_pk_mul_f32 v[40:41], v[0:1], v[40:41] op_sel_hi:[0,1]
	v_pk_mul_f32 v[38:39], v[0:1], v[38:39] op_sel_hi:[0,1]
	v_pk_mul_f32 v[36:37], v[0:1], v[36:37] op_sel_hi:[0,1]
	v_pk_mul_f32 v[34:35], v[0:1], v[34:35] op_sel_hi:[0,1]
	v_pk_mul_f32 v[32:33], v[0:1], v[32:33] op_sel_hi:[0,1]
	v_pk_mul_f32 v[30:31], v[0:1], v[30:31] op_sel_hi:[0,1]
	v_pk_mul_f32 v[28:29], v[0:1], v[28:29] op_sel_hi:[0,1]
	v_pk_mul_f32 v[26:27], v[0:1], v[26:27] op_sel_hi:[0,1]
	v_pk_mul_f32 v[24:25], v[0:1], v[24:25] op_sel_hi:[0,1]
	v_pk_mul_f32 v[22:23], v[0:1], v[22:23] op_sel_hi:[0,1]
	v_pk_mul_f32 v[20:21], v[0:1], v[20:21] op_sel_hi:[0,1]
	v_pk_mul_f32 v[18:19], v[0:1], v[18:19] op_sel_hi:[0,1]
	v_pk_mul_f32 v[16:17], v[0:1], v[16:17] op_sel_hi:[0,1]
.Lav_noscale:
	ds_read_b64_tr_b16 v[240:241], v3 offset:320
	ds_read_b64_tr_b16 v[242:243], v3 offset:5568
	ds_read_b64_tr_b16 v[244:245], v3 offset:384
	ds_read_b64_tr_b16 v[246:247], v3 offset:5632
	ds_read_b64_tr_b16 v[248:249], v3 offset:448
	ds_read_b64_tr_b16 v[250:251], v3 offset:5696
	s_waitcnt lgkmcnt(14)
	v_mfma_f32_32x32x16_bf16 v[128:143], v[220:223], v[176:179], v[128:143]
	ds_read_b64_tr_b16 v[220:221], v3 offset:10496
	ds_read_b64_tr_b16 v[222:223], v3 offset:15744
	s_waitcnt lgkmcnt(14)
	v_mfma_f32_32x32x16_bf16 v[112:127], v[224:227], v[176:179], v[112:127]
	ds_read_b64_tr_b16 v[224:225], v3 offset:10560
	ds_read_b64_tr_b16 v[226:227], v3 offset:15808
	s_waitcnt lgkmcnt(14)
	v_mfma_f32_32x32x16_bf16 v[96:111], v[228:231], v[176:179], v[96:111]
	ds_read_b64_tr_b16 v[228:229], v3 offset:10624
	ds_read_b64_tr_b16 v[230:231], v3 offset:15872
	s_waitcnt lgkmcnt(14)
	v_mfma_f32_32x32x16_bf16 v[80:95], v[232:235], v[176:179], v[80:95]
	ds_read_b64_tr_b16 v[232:233], v3 offset:10688
	ds_read_b64_tr_b16 v[234:235], v3 offset:15936
	s_waitcnt lgkmcnt(14)
	v_mfma_f32_32x32x16_bf16 v[64:79], v[236:239], v[176:179], v[64:79]
	ds_read_b64_tr_b16 v[236:237], v3 offset:10752
	ds_read_b64_tr_b16 v[238:239], v3 offset:16000
	s_waitcnt lgkmcnt(14)
	v_mfma_f32_32x32x16_bf16 v[48:63], v[240:243], v[176:179], v[48:63]
	ds_read_b64_tr_b16 v[240:241], v3 offset:10816
	ds_read_b64_tr_b16 v[242:243], v3 offset:16064
	s_waitcnt lgkmcnt(14)
	v_mfma_f32_32x32x16_bf16 v[32:47], v[244:247], v[176:179], v[32:47]
	ds_read_b64_tr_b16 v[244:245], v3 offset:10880
	ds_read_b64_tr_b16 v[246:247], v3 offset:16128
	s_waitcnt lgkmcnt(14)
	v_mfma_f32_32x32x16_bf16 v[16:31], v[248:251], v[176:179], v[16:31]
	ds_read_b64_tr_b16 v[248:249], v3 offset:10944
	ds_read_b64_tr_b16 v[250:251], v3 offset:16192
	s_waitcnt lgkmcnt(14)
	v_mfma_f32_32x32x16_bf16 v[128:143], v[220:223], v[180:183], v[128:143]
	ds_read_b64_tr_b16 v[220:221], v3 offset:20992
	ds_read_b64_tr_b16 v[222:223], v3 offset:26240
	s_waitcnt lgkmcnt(14)
	v_mfma_f32_32x32x16_bf16 v[112:127], v[224:227], v[180:183], v[112:127]
	ds_read_b64_tr_b16 v[224:225], v3 offset:21056
	ds_read_b64_tr_b16 v[226:227], v3 offset:26304
	s_waitcnt lgkmcnt(14)
	v_mfma_f32_32x32x16_bf16 v[96:111], v[228:231], v[180:183], v[96:111]
	ds_read_b64_tr_b16 v[228:229], v3 offset:21120
	ds_read_b64_tr_b16 v[230:231], v3 offset:26368
	s_waitcnt lgkmcnt(14)
	v_mfma_f32_32x32x16_bf16 v[80:95], v[232:235], v[180:183], v[80:95]
	ds_read_b64_tr_b16 v[232:233], v3 offset:21184
	ds_read_b64_tr_b16 v[234:235], v3 offset:26432
	s_waitcnt vmcnt(0)
	ds_write_b128 v145, v[4:7]
	ds_write_b128 v145, v[8:11] offset:16
	ds_write_b128 v145, v[12:15] offset:32
	ds_write_b128 v145, v[146:149] offset:48
	ds_write_b128 v145, v[150:153] offset:64
	global_load_dwordx4 v[4:7], v[252:253], off offset:80
	global_load_dwordx4 v[8:11], v[252:253], off offset:96
	global_load_dwordx4 v[12:15], v[252:253], off offset:112
	global_load_dwordx4 v[146:149], v[252:253], off offset:128
	global_load_dwordx4 v[150:153], v[252:253], off offset:144
	s_waitcnt lgkmcnt(15)
	v_mfma_f32_32x32x16_bf16 v[64:79], v[236:239], v[180:183], v[64:79]
	ds_read_b64_tr_b16 v[236:237], v3 offset:21248
	ds_read_b64_tr_b16 v[238:239], v3 offset:26496
	s_waitcnt lgkmcnt(15)
	v_mfma_f32_32x32x16_bf16 v[48:63], v[240:243], v[180:183], v[48:63]
	ds_read_b64_tr_b16 v[240:241], v3 offset:21312
	ds_read_b64_tr_b16 v[242:243], v3 offset:26560
	s_waitcnt lgkmcnt(15)
	v_mfma_f32_32x32x16_bf16 v[32:47], v[244:247], v[180:183], v[32:47]
	ds_read_b64_tr_b16 v[244:245], v3 offset:21376
	ds_read_b64_tr_b16 v[246:247], v3 offset:26624
	s_waitcnt lgkmcnt(15)
	v_mfma_f32_32x32x16_bf16 v[16:31], v[248:251], v[180:183], v[16:31]
	ds_read_b64_tr_b16 v[248:249], v3 offset:21440
	ds_read_b64_tr_b16 v[250:251], v3 offset:26688
	s_waitcnt lgkmcnt(15)
	v_mfma_f32_32x32x16_bf16 v[128:143], v[220:223], v[184:187], v[128:143]
	ds_read_b64_tr_b16 v[220:221], v3 offset:31488
	ds_read_b64_tr_b16 v[222:223], v3 offset:36736
	s_waitcnt lgkmcnt(15)
	v_mfma_f32_32x32x16_bf16 v[112:127], v[224:227], v[184:187], v[112:127]
	ds_read_b64_tr_b16 v[224:225], v3 offset:31552
	ds_read_b64_tr_b16 v[226:227], v3 offset:36800
	s_waitcnt lgkmcnt(15)
	v_mfma_f32_32x32x16_bf16 v[96:111], v[228:231], v[184:187], v[96:111]
	ds_read_b64_tr_b16 v[228:229], v3 offset:31616
	ds_read_b64_tr_b16 v[230:231], v3 offset:36864
	s_waitcnt lgkmcnt(15)
	v_mfma_f32_32x32x16_bf16 v[80:95], v[232:235], v[184:187], v[80:95]
	ds_read_b64_tr_b16 v[232:233], v3 offset:31680
	ds_read_b64_tr_b16 v[234:235], v3 offset:36928
	s_waitcnt lgkmcnt(14)
	v_mfma_f32_32x32x16_bf16 v[64:79], v[236:239], v[184:187], v[64:79]
	ds_read_b64_tr_b16 v[236:237], v3 offset:31744
	ds_read_b64_tr_b16 v[238:239], v3 offset:36992
	s_waitcnt lgkmcnt(14)
	v_mfma_f32_32x32x16_bf16 v[48:63], v[240:243], v[184:187], v[48:63]
	ds_read_b64_tr_b16 v[240:241], v3 offset:31808
	ds_read_b64_tr_b16 v[242:243], v3 offset:37056
	s_waitcnt lgkmcnt(14)
	v_mfma_f32_32x32x16_bf16 v[32:47], v[244:247], v[184:187], v[32:47]
	ds_read_b64_tr_b16 v[244:245], v3 offset:31872
	ds_read_b64_tr_b16 v[246:247], v3 offset:37120
	s_waitcnt lgkmcnt(14)
	v_mfma_f32_32x32x16_bf16 v[16:31], v[248:251], v[184:187], v[16:31]
	ds_read_b64_tr_b16 v[248:249], v3 offset:31936
	ds_read_b64_tr_b16 v[250:251], v3 offset:37184
	s_waitcnt lgkmcnt(14)
	v_mfma_f32_32x32x16_bf16 v[128:143], v[220:223], v[188:191], v[128:143]
	s_waitcnt lgkmcnt(12)
	v_mfma_f32_32x32x16_bf16 v[112:127], v[224:227], v[188:191], v[112:127]
	s_waitcnt lgkmcnt(10)
	v_mfma_f32_32x32x16_bf16 v[96:111], v[228:231], v[188:191], v[96:111]
	s_waitcnt lgkmcnt(8)
	v_mfma_f32_32x32x16_bf16 v[80:95], v[232:235], v[188:191], v[80:95]
	s_waitcnt lgkmcnt(6)
	v_mfma_f32_32x32x16_bf16 v[64:79], v[236:239], v[188:191], v[64:79]
	s_waitcnt lgkmcnt(4)
	v_mfma_f32_32x32x16_bf16 v[48:63], v[240:243], v[188:191], v[48:63]
	s_waitcnt lgkmcnt(2)
	v_mfma_f32_32x32x16_bf16 v[32:47], v[244:247], v[188:191], v[32:47]
	s_waitcnt lgkmcnt(0)
	v_mfma_f32_32x32x16_bf16 v[16:31], v[248:251], v[188:191], v[16:31]
	s_waitcnt vmcnt(0)
	ds_write_b128 v145, v[4:7] offset:80
	ds_write_b128 v145, v[8:11] offset:96
	ds_write_b128 v145, v[12:15] offset:112
	ds_write_b128 v145, v[146:149] offset:128
	ds_write_b128 v145, v[150:153] offset:144
	s_mov_b64 s[8:9], 0xa000
	v_lshl_add_u64 v[252:253], v[252:253], 0, s[8:9]
	s_cmp_eq_u32 s30, s27
	s_cbranch_scc1 .Lav_nopf
	global_load_dwordx4 v[4:7], v[252:253], off
	global_load_dwordx4 v[8:11], v[252:253], off offset:16
	global_load_dwordx4 v[12:15], v[252:253], off offset:32
	global_load_dwordx4 v[146:149], v[252:253], off offset:48
	global_load_dwordx4 v[150:153], v[252:253], off offset:64
.Lav_nopf:
	s_waitcnt lgkmcnt(0)
	s_branch .LBB0_401
.Lav_stage0:
	s_add_i32 s8, s19, 2
	s_mul_hi_u32 s9, s8, 0xaaaaaaab
	s_lshr_b32 s9, s9, 1
	s_mul_i32 s9, s9, 3
	s_sub_i32 s8, s8, s9
	s_mul_i32 s8, s8, 0xa400
	v_add_u32_e32 v145, s8, v170
	global_load_dwordx4 v[4:7], v[252:253], off
	global_load_dwordx4 v[8:11], v[252:253], off offset:16
	global_load_dwordx4 v[12:15], v[252:253], off offset:32
	global_load_dwordx4 v[146:149], v[252:253], off offset:48
	global_load_dwordx4 v[150:153], v[252:253], off offset:64
	s_waitcnt vmcnt(0)
	ds_write_b128 v145, v[4:7]
	ds_write_b128 v145, v[8:11] offset:16
	ds_write_b128 v145, v[12:15] offset:32
	ds_write_b128 v145, v[146:149] offset:48
	ds_write_b128 v145, v[150:153] offset:64
	global_load_dwordx4 v[4:7], v[252:253], off offset:80
	global_load_dwordx4 v[8:11], v[252:253], off offset:96
	global_load_dwordx4 v[12:15], v[252:253], off offset:112
	global_load_dwordx4 v[146:149], v[252:253], off offset:128
	global_load_dwordx4 v[150:153], v[252:253], off offset:144
	s_waitcnt vmcnt(0)
	ds_write_b128 v145, v[4:7] offset:80
	ds_write_b128 v145, v[8:11] offset:96
	ds_write_b128 v145, v[12:15] offset:112
	ds_write_b128 v145, v[146:149] offset:128
	ds_write_b128 v145, v[150:153] offset:144
	s_mov_b64 s[8:9], 0xa000
	v_lshl_add_u64 v[252:253], v[252:253], 0, s[8:9]
	global_load_dwordx4 v[4:7], v[252:253], off
	global_load_dwordx4 v[8:11], v[252:253], off offset:16
	global_load_dwordx4 v[12:15], v[252:253], off offset:32
	global_load_dwordx4 v[146:149], v[252:253], off offset:48
	global_load_dwordx4 v[150:153], v[252:253], off offset:64
	s_waitcnt lgkmcnt(0)
